# plus P2 XB tile swizzle extra low bit g(tok>>6) so the gates A-operand ds_read_b128 are bank-conflict-free (conv writes and element reads stay conflict-free)
# baseline (speedup 1.0000x reference)
.LBB0_385:
	s_or_b64 exec, exec, s[10:11]
	v_mov_b32_e32 v121, v11
	v_lshl_add_u64 v[18:19], s[6:7], 0, v[120:121]
	v_lshlrev_b64 v[18:19], 11, v[18:19]
	v_or_b32_e32 v128, 1, v120
	v_mov_b32_e32 v129, v11
	v_lshl_add_u64 v[50:51], v[16:17], 0, v[18:19]
	v_lshl_add_u64 v[18:19], s[6:7], 0, v[128:129]
	v_lshlrev_b64 v[18:19], 11, v[18:19]
	v_or_b32_e32 v130, 2, v120
	v_mov_b32_e32 v131, v11
	v_lshl_add_u64 v[52:53], v[16:17], 0, v[18:19]
	v_lshl_add_u64 v[18:19], s[6:7], 0, v[130:131]
	v_lshlrev_b64 v[18:19], 11, v[18:19]
	v_or_b32_e32 v132, 3, v120
	v_mov_b32_e32 v133, v11
	v_lshl_add_u64 v[54:55], v[16:17], 0, v[18:19]
	v_lshl_add_u64 v[18:19], s[6:7], 0, v[132:133]
	v_or_b32_e32 v134, 7, v48
	v_lshlrev_b64 v[18:19], 11, v[18:19]
	v_add_u32_e32 v136, -3, v134
	v_mov_b32_e32 v137, v11
	v_lshl_add_u64 v[56:57], v[16:17], 0, v[18:19]
	v_lshl_add_u64 v[18:19], s[6:7], 0, v[136:137]
	v_lshlrev_b64 v[18:19], 11, v[18:19]
	v_or_b32_e32 v138, 5, v120
	v_mov_b32_e32 v139, v11
	v_lshl_add_u64 v[58:59], v[16:17], 0, v[18:19]
	v_lshl_add_u64 v[18:19], s[6:7], 0, v[138:139]
	v_lshlrev_b64 v[18:19], 11, v[18:19]
	v_or_b32_e32 v140, 6, v120
	v_mov_b32_e32 v141, v11
	v_lshl_add_u64 v[60:61], v[16:17], 0, v[18:19]
	v_lshl_add_u64 v[18:19], s[6:7], 0, v[140:141]
	v_lshlrev_b64 v[18:19], 11, v[18:19]
	v_mov_b32_e32 v135, v11
	v_lshl_add_u64 v[62:63], v[16:17], 0, v[18:19]
	v_lshl_add_u64 v[18:19], s[6:7], 0, v[134:135]
	v_and_b32_e32 v10, 24, v48
	v_lshlrev_b64 v[18:19], 11, v[18:19]
	v_lshlrev_b32_e32 v10, 1, v10
	s_mov_b32 s8, 0x1999999a
	v_lshl_add_u64 v[64:65], v[16:17], 0, v[18:19]
	v_lshl_add_u64 v[16:17], s[38:39], 0, v[10:11]
	s_mov_b64 s[6:7], 0x1200000
	v_mul_hi_u32 v10, v0, s8
	v_lshl_add_u64 v[142:143], v[16:17], 0, s[6:7]
	v_mul_u32_u24_e32 v16, 10, v10
	v_sub_u32_e32 v16, v0, v16
	v_lshlrev_b32_e32 v153, 3, v10
	v_cmp_lt_u32_e64 s[8:9], 7, v16
	v_lshlrev_b32_e32 v10, 9, v16
	v_lshlrev_b32_e32 v16, 2, v16
	v_and_b32_e32 v66, 4, v16
	global_load_dwordx4 v[16:19], v[50:51], off nt
	s_waitcnt lgkmcnt(0)
	global_load_dwordx4 v[20:23], v[52:53], off nt
	global_load_dwordx4 v[24:27], v[54:55], off nt
	global_load_dwordx4 v[28:31], v[56:57], off nt
	global_load_dwordx4 v[32:35], v[58:59], off nt
	global_load_dwordx4 v[36:39], v[60:61], off nt
	global_load_dwordx4 v[40:43], v[62:63], off nt
	global_load_dwordx4 v[44:47], v[64:65], off nt
	v_and_b32_e32 v10, 0xc00, v10
	v_add_u32_e32 v155, 0xffffff00, v0
	v_and_b32_e32 v49, 15, v0
	v_lshlrev_b32_e32 v50, 4, v155
	s_add_u32 s20, s38, 0x1e00000
	v_lshlrev_b32_e32 v146, 2, v10
	v_lshl_or_b32 v145, s45, 4, v49
	v_lshlrev_b32_e32 v154, 4, v0
	s_addc_u32 s21, s39, 0
	v_mul_u32_u24_e32 v51, 0xa0, v49
	v_add_u32_e32 v10, 0, v50
	s_movk_i32 s12, 0x80
	s_add_u32 s22, s38, 0x2c00000
	v_lshlrev_b32_e32 v54, 4, v145
	v_and_b32_e32 v55, 0xc0, v154
	v_and_b32_e32 v57, 48, v0
	v_lshrrev_b32_e32 v61, 1, v0
	v_xor_b32_e32 v61, v61, v0
	v_and_b32_e32 v59, 4, v61
	v_lshlrev_b32_e32 v59, 2, v59
	v_xor_b32_e32 v57, v57, v59
	v_lshrrev_b32_e32 v156, 4, v198
	v_add_u32_e32 v163, 0x19000, v10
	v_add_u32_e32 v10, 0, v51
	s_addc_u32 s23, s39, 0
	v_bitop3_b32 v60, v57, v55, s12 bitop3:0x36
	v_lshlrev_b32_e32 v144, 6, v156
	v_lshlrev_b32_e32 v62, 1, v145
	s_mov_b32 s12, 0x7ffffff0
	v_add_u32_e32 v164, 0x18000, v10
	v_add_u32_e32 v10, 0, v54
	s_add_u32 s24, s38, 0x1e80000
	v_bitop3_b32 v62, v62, v144, s12 bitop3:0x6c
	v_and_b32_e32 v59, 16, v61
	v_xor_b32_e32 v62, v62, v59
	s_movk_i32 s29, 0x4400
	v_add_u32_e32 v167, 0x19000, v10
	v_mbcnt_lo_u32_b32 v10, -1, 0
	s_addc_u32 s25, s39, 0
	v_lshlrev_b32_e32 v52, 4, v49
	s_movk_i32 s13, 0xc0
	v_and_b32_e32 v48, 0xc0, v48
	s_movk_i32 s28, 0x110
	v_and_or_b32 v56, v0, 3, v55
	v_mad_u32_u24 v62, v156, s29, v62
	v_and_b32_e32 v63, 7, v0
	v_mbcnt_hi_u32_b32 v10, -1, v10
	s_movk_i32 s6, 0xa0
	v_and_b32_e32 v67, 0x180, v0
	s_movk_i32 s10, 0x100
	v_xad_u32 v48, v52, v48, 0
	v_and_b32_e32 v59, 0x80, v61
	v_lshrrev_b32_e32 v59, 3, v59
	v_xor_b32_e32 v48, v48, v59
	v_mul_u32_u24_e32 v52, 0x110, v120
	v_mul_u32_u24_e32 v53, 0x110, v134
	s_add_u32 s26, s38, 0x2e00000
	v_mul_u32_u24_e32 v58, 0x110, v56
	v_bitop3_b32 v59, v57, v55, 64 bitop3:0x36
	v_bitop3_b32 v61, v57, v154, s13 bitop3:0x72
	v_lshl_or_b32 v62, v63, 1, v62
	v_mad_u32_u24 v55, v56, s28, v55
	v_and_or_b32 v10, v10, 64, v49
	v_add_u32_e32 v152, 0x80, v145
	v_cmp_gt_u32_e64 s[6:7], s6, v0
	v_cmp_eq_u32_e64 s[10:11], s10, v67
	s_addc_u32 s27, s39, 0
	v_cmp_gt_u32_e64 s[12:13], 16, v198
	v_add_u32_e32 v157, 0, v62
	v_add3_u32 v158, v55, v57, 0
	v_add3_u32 v159, v58, v59, 0
	v_add3_u32 v160, v58, v60, 0
	v_add3_u32 v161, v58, v61, 0
	v_lshlrev_b32_e32 v148, 2, v66
	s_mov_b32 s28, 0xbfb8aa3b
	s_mov_b32 s29, 0xb2a5705f
	s_mov_b32 s47, 0x42ce8ed0
	s_mov_b32 s49, 0xc2b17218
	s_mov_b32 s51, 0x7f800000
	s_mov_b32 s53, 0x3f2aaaab
	v_mov_b32_e32 v162, 0x3ecc95a3
	s_mov_b32 s55, 0x3f317218
	s_mov_b32 s64, 0x33800000
	s_mov_b32 s46, 0x3fb8aa3b
	v_add_u32_e32 v165, v48, v52
	v_add_u32_e32 v166, v48, v53
	s_mov_b32 s48, 0x3c088889
	s_mov_b32 s50, 0x3d2aaaab
	s_mov_b32 s52, 0x3e2aaaab
	s_mov_b32 s54, 0x43800000
	s_mov_b32 s65, 0x10001000
	s_mov_b32 s66, 0x10003000
	s_mov_b32 s67, 0x10005000
	s_mov_b32 s68, 0x10007000
	v_lshlrev_b32_e32 v168, 2, v10
	v_mov_b32_e32 v169, 0x7f800000
	v_mov_b32_e32 v150, 0x3f317218
	s_mov_b32 s69, s44
	s_mov_b32 s70, s44
	s_branch .LBB0_387
